# P0 weight transpose: 3-slot software pipeline across items/jobs + workgroup LDS exchange so bf16 rows are stored as full 128-B lines
# speedup vs baseline: 1.0112x; 1.0112x over previous
.LBB0_5:
	s_or_b64 exec, exec, s[6:7]
	s_lshl_b32 s10, s2, 3
	s_lshl_b32 s6, s28, 3
	s_add_u32 s4, s26, 0x1a620000
	v_writelane_b32 v252, s4, 18
	s_addc_u32 s4, s27, 0
	v_writelane_b32 v252, s4, 19
	s_add_u32 s4, s26, 0x18620000
	v_writelane_b32 v252, s4, 20
	s_addc_u32 s4, s27, 0
	v_writelane_b32 v252, s4, 21
	s_add_u32 s4, s26, 0x18420000
	v_writelane_b32 v252, s4, 22
	s_addc_u32 s4, s27, 0
	v_writelane_b32 v252, s4, 23
	s_add_u32 s4, s26, 0x18320000
	v_writelane_b32 v252, s4, 24
	s_addc_u32 s4, s27, 0
	v_writelane_b32 v252, s4, 25
	s_add_u32 s4, s26, 0x18200000
	v_writelane_b32 v252, s4, 26
	s_addc_u32 s4, s27, 0
	v_writelane_b32 v252, s4, 27
	s_add_u32 s4, s26, 0x17f00000
	v_writelane_b32 v252, s4, 28
	s_addc_u32 s4, s27, 0
	v_writelane_b32 v252, s4, 29
	s_add_u32 s4, s26, 0x17c00000
	v_writelane_b32 v252, s4, 30
	s_addc_u32 s4, s27, 0
	v_writelane_b32 v252, s4, 31
	s_add_u32 s4, s26, 0x17000000
	v_writelane_b32 v252, s4, 32
	s_addc_u32 s4, s27, 0
	s_abs_i32 s22, s6
	v_cvt_f32_u32_e32 v2, s22
	v_writelane_b32 v252, s4, 33
	s_mov_b32 s4, s10
	v_mov_b32_e32 v1, v184
	v_rcp_iflag_f32_e32 v2, v2
	v_writelane_b32 v252, s4, 34
	s_lshl_b32 s31, s28, 11
	v_mul_f32_e32 v2, 0x4f7ffffe, v2
	v_cvt_u32_f32_e32 v2, v2
	v_ashrrev_i32_e32 v3, 6, v1
	v_writelane_b32 v252, s5, 35
	s_mov_b32 s4, s6
	v_add_u32_e32 v35, s10, v3
	v_writelane_b32 v252, s4, 36
	v_add_u32_e32 v42, s6, v35
	v_readfirstlane_b32 s6, v2
	v_writelane_b32 v252, s5, 37
	s_sub_i32 s4, 0, s22
	s_mul_i32 s4, s4, s6
	v_and_b32_e32 v37, 63, v1
	s_mul_hi_u32 s4, s6, s4
	v_lshlrev_b32_e32 v34, 2, v37
	s_add_i32 s23, s6, s4
	v_mov_b32_e32 v43, 0
	s_mov_b32 s33, 0
	s_mov_b32 s34, 0
	s_mov_b32 s94, 0
	s_mov_b32 s95, 0
	v_lshlrev_b32_e32 v36, 2, v34
	v_readlane_b32 s70, v252, 36
	v_lshrrev_b32_e32 v219, 6, v184
	v_and_b32_e32 v218, 7, v37
	v_lshlrev_b32_e32 v218, 4, v218
	v_readfirstlane_b32 s99, v219
	v_lshlrev_b32_e32 v220, 4, v219
	v_mul_u32_u24_e32 v221, 0x240, v37
	v_add_u32_e32 v220, v220, v221
	v_lshrrev_b32_e32 v223, 3, v37
	v_lshl_add_u32 v219, v219, 5, v223
	v_mul_u32_u24_e32 v223, 0x90, v219
	v_add_u32_e32 v223, v223, v218
	v_add_u32_e32 v221, 0x9000, v220
	v_add_u32_e32 v222, 0x12000, v220
	v_add_u32_e32 v224, 0x9000, v223
	v_add_u32_e32 v225, 0x12000, v223
	s_branch .LBB0_7

.LBB0_34:
	s_lshr_b32 s14, s52, 3
	s_mul_i32 s53, s4, s14
	s_mul_hi_u32 s14, s33, s23
	s_mul_i32 s14, s14, s22
	s_sub_i32 s14, s33, s14
	s_sub_i32 s15, s14, s22
	s_cmp_ge_u32 s14, s22
	s_cselect_b32 s14, s15, s14
	s_sub_i32 s15, s14, s22
	s_cmp_ge_u32 s14, s22
	s_cselect_b32 s14, s15, s14
	v_subrev_u32_e32 v3, s14, v42
	v_sub_u32_e32 v4, 0, v3
	v_ashrrev_i32_e32 v2, 31, v3
	v_max_i32_e32 v3, v3, v4
	v_mul_hi_u32 v4, v3, s23
	v_mul_lo_u32 v4, v4, s22
	v_sub_u32_e32 v3, v3, v4
	v_subrev_u32_e32 v4, s22, v3
	v_cmp_le_u32_e32 vcc, s22, v3
	s_nop 1
	v_cndmask_b32_e32 v3, v3, v4, vcc
	v_subrev_u32_e32 v4, s22, v3
	v_cmp_le_u32_e32 vcc, s22, v3
	s_nop 1
	v_cndmask_b32_e32 v3, v3, v4, vcc
	v_xor_b32_e32 v3, v3, v2
	v_sub_u32_e32 v44, v3, v2
	v_cmp_gt_i32_e32 vcc, s53, v44
	s_and_saveexec_b64 s[14:15], vcc
	s_cbranch_execz .LBB0_6
	s_lshr_b32 s96, s52, 3
	v_cvt_f32_u32_e32 v4, s96
	s_sub_i32 s20, 0, s96
	v_rcp_iflag_f32_e32 v4, v4
	s_nop 0
	v_mul_f32_e32 v4, 0x4f7ffffe, v4
	v_cvt_u32_f32_e32 v4, v4
	v_mul_lo_u32 v2, s20, v4
	v_mul_hi_u32 v2, v4, v2
	v_add_u32_e32 v45, v4, v2
	s_nop 1
	v_readfirstlane_b32 s69, v45
	v_readfirstlane_b32 s68, v44
	s_nop 3
.Lw_item:
	s_cmp_eq_u32 s95, 1
	s_cbranch_scc1 .Lw_issue1
	s_cmp_eq_u32 s95, 2
	s_cbranch_scc1 .Lw_issue2
.Lw_issue0:
	s_mul_hi_u32 s73, s68, s69
	s_mul_i32 s74, s73, s96
	s_sub_u32 s74, s68, s74
	s_sub_u32 s75, s74, s96
	s_cmp_ge_u32 s74, s96
	s_cselect_b32 s74, s75, s74
	s_addc_u32 s73, s73, 0
	s_sub_u32 s75, s74, s96
	s_cmp_ge_u32 s74, s96
	s_cselect_b32 s74, s75, s74
	s_addc_u32 s73, s73, 0
	s_lshl_b32 s75, s74, 3
	s_lshl_b32 s78, s52, 1
	s_lshl_b32 s71, s99, 3
	s_sub_u32 s71, s75, s71
	s_lshl_b32 s71, s71, 1
	s_add_u32 s76, s10, s71
	s_addc_u32 s77, s11, 0
	s_mul_i32 s71, s73, s52
	s_lshl_b32 s71, s71, 9
	s_add_u32 s76, s76, s71
	s_addc_u32 s77, s77, 0
	v_mul_lo_u32 v96, v219, s78
	v_add_u32_e32 v96, v96, v218
	s_mul_i32 s71, s75, s35
	s_lshl_b32 s97, s73, 8
	s_add_u32 s71, s71, s97
	s_lshl_b32 s71, s71, 2
	s_add_u32 s84, s6, s71
	s_addc_u32 s85, s7, 0
	s_lshl_b32 s72, s35, 2
	s_add_i32 s71, s97, 0x100
	s_cmp_le_u32 s71, s35
	s_cbranch_scc1 .Lw_inr_i0
	v_mov_b32_e32 v56, 0
	v_mov_b32_e32 v57, 0
	v_mov_b32_e32 v58, 0
	v_mov_b32_e32 v59, 0
	v_mov_b32_e32 v60, 0
	v_mov_b32_e32 v61, 0
	v_mov_b32_e32 v62, 0
	v_mov_b32_e32 v63, 0
	v_mov_b32_e32 v64, 0
	v_mov_b32_e32 v65, 0
	v_mov_b32_e32 v66, 0
	v_mov_b32_e32 v67, 0
	v_mov_b32_e32 v68, 0
	v_mov_b32_e32 v69, 0
	v_mov_b32_e32 v70, 0
	v_mov_b32_e32 v71, 0
	v_mov_b32_e32 v72, 0
	v_mov_b32_e32 v73, 0
	v_mov_b32_e32 v74, 0
	v_mov_b32_e32 v75, 0
	v_mov_b32_e32 v76, 0
	v_mov_b32_e32 v77, 0
	v_mov_b32_e32 v78, 0
	v_mov_b32_e32 v79, 0
	v_mov_b32_e32 v80, 0
	v_mov_b32_e32 v81, 0
	v_mov_b32_e32 v82, 0
	v_mov_b32_e32 v83, 0
	v_mov_b32_e32 v84, 0
	v_mov_b32_e32 v85, 0
	v_mov_b32_e32 v86, 0
	v_mov_b32_e32 v87, 0
	s_sub_u32 s71, s35, s97
	v_cmp_gt_u32_e32 vcc, s71, v34
	s_nop 3
	s_mov_b64 exec, vcc
.Lw_inr_i0:
	global_load_dwordx4 v[56:59], v36, s[84:85] nt
	s_add_u32 s84, s84, s72
	s_addc_u32 s85, s85, 0
	global_load_dwordx4 v[60:63], v36, s[84:85] nt
	s_add_u32 s84, s84, s72
	s_addc_u32 s85, s85, 0
	global_load_dwordx4 v[64:67], v36, s[84:85] nt
	s_add_u32 s84, s84, s72
	s_addc_u32 s85, s85, 0
	global_load_dwordx4 v[68:71], v36, s[84:85] nt
	s_add_u32 s84, s84, s72
	s_addc_u32 s85, s85, 0
	global_load_dwordx4 v[72:75], v36, s[84:85] nt
	s_add_u32 s84, s84, s72
	s_addc_u32 s85, s85, 0
	global_load_dwordx4 v[76:79], v36, s[84:85] nt
	s_add_u32 s84, s84, s72
	s_addc_u32 s85, s85, 0
	global_load_dwordx4 v[80:83], v36, s[84:85] nt
	s_add_u32 s84, s84, s72
	s_addc_u32 s85, s85, 0
	global_load_dwordx4 v[84:87], v36, s[84:85] nt
	s_mov_b64 exec, -1
	s_lshl_b32 s71, s75, 2
	s_add_u32 s84, s12, s71
	s_addc_u32 s85, s13, 0
	s_mov_b32 s79, 1
	s_cmp_lg_u64 s[12:13], 0
	s_cbranch_scc1 .Lw_hg_i0
	s_mov_b64 s[84:85], s[6:7]
	s_mov_b32 s79, 0
.Lw_hg_i0:
	global_load_dwordx4 v[88:91], v43, s[84:85]
	global_load_dwordx4 v[92:95], v43, s[84:85] offset:16
	s_add_i32 s94, s94, 1
	s_cmp_lt_u32 s94, 3
	s_cbranch_scc1 .Lw_next0
	s_waitcnt vmcnt(20)
	s_cmp_eq_u32 s83, 0
	s_cbranch_scc1 .Lw_ng_s0
	v_mul_f32_e32 v98, v98, v130
	v_mul_f32_e32 v99, v99, v130
	v_mul_f32_e32 v100, v100, v130
	v_mul_f32_e32 v101, v101, v130
	v_mul_f32_e32 v102, v102, v131
	v_mul_f32_e32 v103, v103, v131
	v_mul_f32_e32 v104, v104, v131
	v_mul_f32_e32 v105, v105, v131
	v_mul_f32_e32 v106, v106, v132
	v_mul_f32_e32 v107, v107, v132
	v_mul_f32_e32 v108, v108, v132
	v_mul_f32_e32 v109, v109, v132
	v_mul_f32_e32 v110, v110, v133
	v_mul_f32_e32 v111, v111, v133
	v_mul_f32_e32 v112, v112, v133
	v_mul_f32_e32 v113, v113, v133
	v_mul_f32_e32 v114, v114, v134
	v_mul_f32_e32 v115, v115, v134
	v_mul_f32_e32 v116, v116, v134
	v_mul_f32_e32 v117, v117, v134
	v_mul_f32_e32 v118, v118, v135
	v_mul_f32_e32 v119, v119, v135
	v_mul_f32_e32 v120, v120, v135
	v_mul_f32_e32 v121, v121, v135
	v_mul_f32_e32 v122, v122, v136
	v_mul_f32_e32 v123, v123, v136
	v_mul_f32_e32 v124, v124, v136
	v_mul_f32_e32 v125, v125, v136
	v_mul_f32_e32 v126, v126, v137
	v_mul_f32_e32 v127, v127, v137
	v_mul_f32_e32 v128, v128, v137
	v_mul_f32_e32 v129, v129, v137
.Lw_ng_s0:
	s_mov_b64 s[92:93], s[80:81]
	v_cvt_pk_bf16_f32 v186, v98, v102
	v_cvt_pk_bf16_f32 v187, v106, v110
	v_cvt_pk_bf16_f32 v188, v114, v118
	v_cvt_pk_bf16_f32 v189, v122, v126
	v_cvt_pk_bf16_f32 v190, v99, v103
	v_cvt_pk_bf16_f32 v191, v107, v111
	v_cvt_pk_bf16_f32 v192, v115, v119
	v_cvt_pk_bf16_f32 v193, v123, v127
	v_cvt_pk_bf16_f32 v194, v100, v104
	v_cvt_pk_bf16_f32 v195, v108, v112
	v_cvt_pk_bf16_f32 v196, v116, v120
	v_cvt_pk_bf16_f32 v197, v124, v128
	v_cvt_pk_bf16_f32 v198, v101, v105
	v_cvt_pk_bf16_f32 v199, v109, v113
	v_cvt_pk_bf16_f32 v200, v117, v121
	v_cvt_pk_bf16_f32 v201, v125, v129
	ds_write_b128 v221, v[186:189] offset:0
	ds_write_b128 v221, v[190:193] offset:144
	ds_write_b128 v221, v[194:197] offset:288
	ds_write_b128 v221, v[198:201] offset:432
	s_lshl_b32 s97, s82, 3
	s_waitcnt lgkmcnt(0)
	s_barrier
	ds_read_b128 v[202:205], v224 offset:0
	ds_read_b128 v[206:209], v224 offset:1152
	ds_read_b128 v[210:213], v224 offset:2304
	ds_read_b128 v[214:217], v224 offset:3456
	s_waitcnt lgkmcnt(0)
	global_store_dwordx4 v138, v[202:205], s[92:93]
	s_add_u32 s92, s92, s97
	s_addc_u32 s93, s93, 0
	global_store_dwordx4 v138, v[206:209], s[92:93]
	s_add_u32 s92, s92, s97
	s_addc_u32 s93, s93, 0
	global_store_dwordx4 v138, v[210:213], s[92:93]
	s_add_u32 s92, s92, s97
	s_addc_u32 s93, s93, 0
	global_store_dwordx4 v138, v[214:217], s[92:93]
	s_mov_b32 s94, 2
.Lw_next0:
	s_mov_b32 s95, 1
	s_add_i32 s68, s68, s70
	s_cmp_lt_i32 s68, s53
	s_cbranch_scc1 .Lw_item
	s_branch .LBB0_6
.Lw_issue1:
	s_mul_hi_u32 s73, s68, s69
	s_mul_i32 s74, s73, s96
	s_sub_u32 s74, s68, s74
	s_sub_u32 s75, s74, s96
	s_cmp_ge_u32 s74, s96
	s_cselect_b32 s74, s75, s74
	s_addc_u32 s73, s73, 0
	s_sub_u32 s75, s74, s96
	s_cmp_ge_u32 s74, s96
	s_cselect_b32 s74, s75, s74
	s_addc_u32 s73, s73, 0
	s_lshl_b32 s75, s74, 3
	s_lshl_b32 s82, s52, 1
	s_lshl_b32 s71, s99, 3
	s_sub_u32 s71, s75, s71
	s_lshl_b32 s71, s71, 1
	s_add_u32 s80, s10, s71
	s_addc_u32 s81, s11, 0
	s_mul_i32 s71, s73, s52
	s_lshl_b32 s71, s71, 9
	s_add_u32 s80, s80, s71
	s_addc_u32 s81, s81, 0
	v_mul_lo_u32 v138, v219, s82
	v_add_u32_e32 v138, v138, v218
	s_mul_i32 s71, s75, s35
	s_lshl_b32 s97, s73, 8
	s_add_u32 s71, s71, s97
	s_lshl_b32 s71, s71, 2
	s_add_u32 s84, s6, s71
	s_addc_u32 s85, s7, 0
	s_lshl_b32 s72, s35, 2
	s_add_i32 s71, s97, 0x100
	s_cmp_le_u32 s71, s35
	s_cbranch_scc1 .Lw_inr_i1
	v_mov_b32_e32 v98, 0
	v_mov_b32_e32 v99, 0
	v_mov_b32_e32 v100, 0
	v_mov_b32_e32 v101, 0
	v_mov_b32_e32 v102, 0
	v_mov_b32_e32 v103, 0
	v_mov_b32_e32 v104, 0
	v_mov_b32_e32 v105, 0
	v_mov_b32_e32 v106, 0
	v_mov_b32_e32 v107, 0
	v_mov_b32_e32 v108, 0
	v_mov_b32_e32 v109, 0
	v_mov_b32_e32 v110, 0
	v_mov_b32_e32 v111, 0
	v_mov_b32_e32 v112, 0
	v_mov_b32_e32 v113, 0
	v_mov_b32_e32 v114, 0
	v_mov_b32_e32 v115, 0
	v_mov_b32_e32 v116, 0
	v_mov_b32_e32 v117, 0
	v_mov_b32_e32 v118, 0
	v_mov_b32_e32 v119, 0
	v_mov_b32_e32 v120, 0
	v_mov_b32_e32 v121, 0
	v_mov_b32_e32 v122, 0
	v_mov_b32_e32 v123, 0
	v_mov_b32_e32 v124, 0
	v_mov_b32_e32 v125, 0
	v_mov_b32_e32 v126, 0
	v_mov_b32_e32 v127, 0
	v_mov_b32_e32 v128, 0
	v_mov_b32_e32 v129, 0
	s_sub_u32 s71, s35, s97
	v_cmp_gt_u32_e32 vcc, s71, v34
	s_nop 3
	s_mov_b64 exec, vcc
.Lw_inr_i1:
	global_load_dwordx4 v[98:101], v36, s[84:85] nt
	s_add_u32 s84, s84, s72
	s_addc_u32 s85, s85, 0
	global_load_dwordx4 v[102:105], v36, s[84:85] nt
	s_add_u32 s84, s84, s72
	s_addc_u32 s85, s85, 0
	global_load_dwordx4 v[106:109], v36, s[84:85] nt
	s_add_u32 s84, s84, s72
	s_addc_u32 s85, s85, 0
	global_load_dwordx4 v[110:113], v36, s[84:85] nt
	s_add_u32 s84, s84, s72
	s_addc_u32 s85, s85, 0
	global_load_dwordx4 v[114:117], v36, s[84:85] nt
	s_add_u32 s84, s84, s72
	s_addc_u32 s85, s85, 0
	global_load_dwordx4 v[118:121], v36, s[84:85] nt
	s_add_u32 s84, s84, s72
	s_addc_u32 s85, s85, 0
	global_load_dwordx4 v[122:125], v36, s[84:85] nt
	s_add_u32 s84, s84, s72
	s_addc_u32 s85, s85, 0
	global_load_dwordx4 v[126:129], v36, s[84:85] nt
	s_mov_b64 exec, -1
	s_lshl_b32 s71, s75, 2
	s_add_u32 s84, s12, s71
	s_addc_u32 s85, s13, 0
	s_mov_b32 s83, 1
	s_cmp_lg_u64 s[12:13], 0
	s_cbranch_scc1 .Lw_hg_i1
	s_mov_b64 s[84:85], s[6:7]
	s_mov_b32 s83, 0
.Lw_hg_i1:
	global_load_dwordx4 v[130:133], v43, s[84:85]
	global_load_dwordx4 v[134:137], v43, s[84:85] offset:16
	s_add_i32 s94, s94, 1
	s_cmp_lt_u32 s94, 3
	s_cbranch_scc1 .Lw_next1
	s_waitcnt vmcnt(20)
	s_cmp_eq_u32 s91, 0
	s_cbranch_scc1 .Lw_ng_s1
	v_mul_f32_e32 v140, v140, v172
	v_mul_f32_e32 v141, v141, v172
	v_mul_f32_e32 v142, v142, v172
	v_mul_f32_e32 v143, v143, v172
	v_mul_f32_e32 v144, v144, v173
	v_mul_f32_e32 v145, v145, v173
	v_mul_f32_e32 v146, v146, v173
	v_mul_f32_e32 v147, v147, v173
	v_mul_f32_e32 v148, v148, v174
	v_mul_f32_e32 v149, v149, v174
	v_mul_f32_e32 v150, v150, v174
	v_mul_f32_e32 v151, v151, v174
	v_mul_f32_e32 v152, v152, v175
	v_mul_f32_e32 v153, v153, v175
	v_mul_f32_e32 v154, v154, v175
	v_mul_f32_e32 v155, v155, v175
	v_mul_f32_e32 v156, v156, v176
	v_mul_f32_e32 v157, v157, v176
	v_mul_f32_e32 v158, v158, v176
	v_mul_f32_e32 v159, v159, v176
	v_mul_f32_e32 v160, v160, v177
	v_mul_f32_e32 v161, v161, v177
	v_mul_f32_e32 v162, v162, v177
	v_mul_f32_e32 v163, v163, v177
	v_mul_f32_e32 v164, v164, v178
	v_mul_f32_e32 v165, v165, v178
	v_mul_f32_e32 v166, v166, v178
	v_mul_f32_e32 v167, v167, v178
	v_mul_f32_e32 v168, v168, v179
	v_mul_f32_e32 v169, v169, v179
	v_mul_f32_e32 v170, v170, v179
	v_mul_f32_e32 v171, v171, v179
.Lw_ng_s1:
	s_mov_b64 s[92:93], s[88:89]
	v_cvt_pk_bf16_f32 v186, v140, v144
	v_cvt_pk_bf16_f32 v187, v148, v152
	v_cvt_pk_bf16_f32 v188, v156, v160
	v_cvt_pk_bf16_f32 v189, v164, v168
	v_cvt_pk_bf16_f32 v190, v141, v145
	v_cvt_pk_bf16_f32 v191, v149, v153
	v_cvt_pk_bf16_f32 v192, v157, v161
	v_cvt_pk_bf16_f32 v193, v165, v169
	v_cvt_pk_bf16_f32 v194, v142, v146
	v_cvt_pk_bf16_f32 v195, v150, v154
	v_cvt_pk_bf16_f32 v196, v158, v162
	v_cvt_pk_bf16_f32 v197, v166, v170
	v_cvt_pk_bf16_f32 v198, v143, v147
	v_cvt_pk_bf16_f32 v199, v151, v155
	v_cvt_pk_bf16_f32 v200, v159, v163
	v_cvt_pk_bf16_f32 v201, v167, v171
	ds_write_b128 v222, v[186:189] offset:0
	ds_write_b128 v222, v[190:193] offset:144
	ds_write_b128 v222, v[194:197] offset:288
	ds_write_b128 v222, v[198:201] offset:432
	s_lshl_b32 s97, s90, 3
	s_waitcnt lgkmcnt(0)
	s_barrier
	ds_read_b128 v[202:205], v225 offset:0
	ds_read_b128 v[206:209], v225 offset:1152
	ds_read_b128 v[210:213], v225 offset:2304
	ds_read_b128 v[214:217], v225 offset:3456
	s_waitcnt lgkmcnt(0)
	global_store_dwordx4 v180, v[202:205], s[92:93]
	s_add_u32 s92, s92, s97
	s_addc_u32 s93, s93, 0
	global_store_dwordx4 v180, v[206:209], s[92:93]
	s_add_u32 s92, s92, s97
	s_addc_u32 s93, s93, 0
	global_store_dwordx4 v180, v[210:213], s[92:93]
	s_add_u32 s92, s92, s97
	s_addc_u32 s93, s93, 0
	global_store_dwordx4 v180, v[214:217], s[92:93]
	s_mov_b32 s94, 2
.Lw_next1:
	s_mov_b32 s95, 2
	s_add_i32 s68, s68, s70
	s_cmp_lt_i32 s68, s53
	s_cbranch_scc1 .Lw_item
	s_branch .LBB0_6
.Lw_issue2:
	s_mul_hi_u32 s73, s68, s69
	s_mul_i32 s74, s73, s96
	s_sub_u32 s74, s68, s74
	s_sub_u32 s75, s74, s96
	s_cmp_ge_u32 s74, s96
	s_cselect_b32 s74, s75, s74
	s_addc_u32 s73, s73, 0
	s_sub_u32 s75, s74, s96
	s_cmp_ge_u32 s74, s96
	s_cselect_b32 s74, s75, s74
	s_addc_u32 s73, s73, 0
	s_lshl_b32 s75, s74, 3
	s_lshl_b32 s90, s52, 1
	s_lshl_b32 s71, s99, 3
	s_sub_u32 s71, s75, s71
	s_lshl_b32 s71, s71, 1
	s_add_u32 s88, s10, s71
	s_addc_u32 s89, s11, 0
	s_mul_i32 s71, s73, s52
	s_lshl_b32 s71, s71, 9
	s_add_u32 s88, s88, s71
	s_addc_u32 s89, s89, 0
	v_mul_lo_u32 v180, v219, s90
	v_add_u32_e32 v180, v180, v218
	s_mul_i32 s71, s75, s35
	s_lshl_b32 s97, s73, 8
	s_add_u32 s71, s71, s97
	s_lshl_b32 s71, s71, 2
	s_add_u32 s84, s6, s71
	s_addc_u32 s85, s7, 0
	s_lshl_b32 s72, s35, 2
	s_add_i32 s71, s97, 0x100
	s_cmp_le_u32 s71, s35
	s_cbranch_scc1 .Lw_inr_i2
	v_mov_b32_e32 v140, 0
	v_mov_b32_e32 v141, 0
	v_mov_b32_e32 v142, 0
	v_mov_b32_e32 v143, 0
	v_mov_b32_e32 v144, 0
	v_mov_b32_e32 v145, 0
	v_mov_b32_e32 v146, 0
	v_mov_b32_e32 v147, 0
	v_mov_b32_e32 v148, 0
	v_mov_b32_e32 v149, 0
	v_mov_b32_e32 v150, 0
	v_mov_b32_e32 v151, 0
	v_mov_b32_e32 v152, 0
	v_mov_b32_e32 v153, 0
	v_mov_b32_e32 v154, 0
	v_mov_b32_e32 v155, 0
	v_mov_b32_e32 v156, 0
	v_mov_b32_e32 v157, 0
	v_mov_b32_e32 v158, 0
	v_mov_b32_e32 v159, 0
	v_mov_b32_e32 v160, 0
	v_mov_b32_e32 v161, 0
	v_mov_b32_e32 v162, 0
	v_mov_b32_e32 v163, 0
	v_mov_b32_e32 v164, 0
	v_mov_b32_e32 v165, 0
	v_mov_b32_e32 v166, 0
	v_mov_b32_e32 v167, 0
	v_mov_b32_e32 v168, 0
	v_mov_b32_e32 v169, 0
	v_mov_b32_e32 v170, 0
	v_mov_b32_e32 v171, 0
	s_sub_u32 s71, s35, s97
	v_cmp_gt_u32_e32 vcc, s71, v34
	s_nop 3
	s_mov_b64 exec, vcc
.Lw_inr_i2:
	global_load_dwordx4 v[140:143], v36, s[84:85] nt
	s_add_u32 s84, s84, s72
	s_addc_u32 s85, s85, 0
	global_load_dwordx4 v[144:147], v36, s[84:85] nt
	s_add_u32 s84, s84, s72
	s_addc_u32 s85, s85, 0
	global_load_dwordx4 v[148:151], v36, s[84:85] nt
	s_add_u32 s84, s84, s72
	s_addc_u32 s85, s85, 0
	global_load_dwordx4 v[152:155], v36, s[84:85] nt
	s_add_u32 s84, s84, s72
	s_addc_u32 s85, s85, 0
	global_load_dwordx4 v[156:159], v36, s[84:85] nt
	s_add_u32 s84, s84, s72
	s_addc_u32 s85, s85, 0
	global_load_dwordx4 v[160:163], v36, s[84:85] nt
	s_add_u32 s84, s84, s72
	s_addc_u32 s85, s85, 0
	global_load_dwordx4 v[164:167], v36, s[84:85] nt
	s_add_u32 s84, s84, s72
	s_addc_u32 s85, s85, 0
	global_load_dwordx4 v[168:171], v36, s[84:85] nt
	s_mov_b64 exec, -1
	s_lshl_b32 s71, s75, 2
	s_add_u32 s84, s12, s71
	s_addc_u32 s85, s13, 0
	s_mov_b32 s91, 1
	s_cmp_lg_u64 s[12:13], 0
	s_cbranch_scc1 .Lw_hg_i2
	s_mov_b64 s[84:85], s[6:7]
	s_mov_b32 s91, 0
.Lw_hg_i2:
	global_load_dwordx4 v[172:175], v43, s[84:85]
	global_load_dwordx4 v[176:179], v43, s[84:85] offset:16
	s_add_i32 s94, s94, 1
	s_cmp_lt_u32 s94, 3
	s_cbranch_scc1 .Lw_next2
	s_waitcnt vmcnt(20)
	s_cmp_eq_u32 s79, 0
	s_cbranch_scc1 .Lw_ng_s2
	v_mul_f32_e32 v56, v56, v88
	v_mul_f32_e32 v57, v57, v88
	v_mul_f32_e32 v58, v58, v88
	v_mul_f32_e32 v59, v59, v88
	v_mul_f32_e32 v60, v60, v89
	v_mul_f32_e32 v61, v61, v89
	v_mul_f32_e32 v62, v62, v89
	v_mul_f32_e32 v63, v63, v89
	v_mul_f32_e32 v64, v64, v90
	v_mul_f32_e32 v65, v65, v90
	v_mul_f32_e32 v66, v66, v90
	v_mul_f32_e32 v67, v67, v90
	v_mul_f32_e32 v68, v68, v91
	v_mul_f32_e32 v69, v69, v91
	v_mul_f32_e32 v70, v70, v91
	v_mul_f32_e32 v71, v71, v91
	v_mul_f32_e32 v72, v72, v92
	v_mul_f32_e32 v73, v73, v92
	v_mul_f32_e32 v74, v74, v92
	v_mul_f32_e32 v75, v75, v92
	v_mul_f32_e32 v76, v76, v93
	v_mul_f32_e32 v77, v77, v93
	v_mul_f32_e32 v78, v78, v93
	v_mul_f32_e32 v79, v79, v93
	v_mul_f32_e32 v80, v80, v94
	v_mul_f32_e32 v81, v81, v94
	v_mul_f32_e32 v82, v82, v94
	v_mul_f32_e32 v83, v83, v94
	v_mul_f32_e32 v84, v84, v95
	v_mul_f32_e32 v85, v85, v95
	v_mul_f32_e32 v86, v86, v95
	v_mul_f32_e32 v87, v87, v95
.Lw_ng_s2:
	s_mov_b64 s[92:93], s[76:77]
	v_cvt_pk_bf16_f32 v186, v56, v60
	v_cvt_pk_bf16_f32 v187, v64, v68
	v_cvt_pk_bf16_f32 v188, v72, v76
	v_cvt_pk_bf16_f32 v189, v80, v84
	v_cvt_pk_bf16_f32 v190, v57, v61
	v_cvt_pk_bf16_f32 v191, v65, v69
	v_cvt_pk_bf16_f32 v192, v73, v77
	v_cvt_pk_bf16_f32 v193, v81, v85
	v_cvt_pk_bf16_f32 v194, v58, v62
	v_cvt_pk_bf16_f32 v195, v66, v70
	v_cvt_pk_bf16_f32 v196, v74, v78
	v_cvt_pk_bf16_f32 v197, v82, v86
	v_cvt_pk_bf16_f32 v198, v59, v63
	v_cvt_pk_bf16_f32 v199, v67, v71
	v_cvt_pk_bf16_f32 v200, v75, v79
	v_cvt_pk_bf16_f32 v201, v83, v87
	ds_write_b128 v220, v[186:189] offset:0
	ds_write_b128 v220, v[190:193] offset:144
	ds_write_b128 v220, v[194:197] offset:288
	ds_write_b128 v220, v[198:201] offset:432
	s_lshl_b32 s97, s78, 3
	s_waitcnt lgkmcnt(0)
	s_barrier
	ds_read_b128 v[202:205], v223 offset:0
	ds_read_b128 v[206:209], v223 offset:1152
	ds_read_b128 v[210:213], v223 offset:2304
	ds_read_b128 v[214:217], v223 offset:3456
	s_waitcnt lgkmcnt(0)
	global_store_dwordx4 v96, v[202:205], s[92:93]
	s_add_u32 s92, s92, s97
	s_addc_u32 s93, s93, 0
	global_store_dwordx4 v96, v[206:209], s[92:93]
	s_add_u32 s92, s92, s97
	s_addc_u32 s93, s93, 0
	global_store_dwordx4 v96, v[210:213], s[92:93]
	s_add_u32 s92, s92, s97
	s_addc_u32 s93, s93, 0
	global_store_dwordx4 v96, v[214:217], s[92:93]
	s_mov_b32 s94, 2
.Lw_next2:
	s_mov_b32 s95, 0
	s_add_i32 s68, s68, s70
	s_cmp_lt_i32 s68, s53
	s_cbranch_scc1 .Lw_item
	s_branch .LBB0_6
.LBB0_42:
	s_movk_i32 s52, 0x1000
	s_movk_i32 s35, 0x400
	s_mov_b32 s4, 4
	s_mov_b64 s[12:13], 0
	s_andn2_b64 vcc, exec, s[14:15]
	s_cbranch_vccz .LBB0_18
	s_branch .LBB0_19
.LBB0_43:
	s_waitcnt vmcnt(0)
.Lw_flush:
	s_cmp_eq_u32 s94, 0
	s_cbranch_scc1 .Lw_flushed
	s_sub_i32 s71, s95, s94
	s_add_i32 s97, s71, 3
	s_cmp_lt_i32 s71, 0
	s_cselect_b32 s71, s97, s71
	s_sub_i32 s94, s94, 1
	s_cmp_eq_u32 s71, 1
	s_cbranch_scc1 .Lw_fl1
	s_cmp_eq_u32 s71, 2
	s_cbranch_scc1 .Lw_fl2
.Lw_fl0:
	s_cmp_eq_u32 s79, 0
	s_cbranch_scc1 .Lw_ng_f0
	v_mul_f32_e32 v56, v56, v88
	v_mul_f32_e32 v57, v57, v88
	v_mul_f32_e32 v58, v58, v88
	v_mul_f32_e32 v59, v59, v88
	v_mul_f32_e32 v60, v60, v89
	v_mul_f32_e32 v61, v61, v89
	v_mul_f32_e32 v62, v62, v89
	v_mul_f32_e32 v63, v63, v89
	v_mul_f32_e32 v64, v64, v90
	v_mul_f32_e32 v65, v65, v90
	v_mul_f32_e32 v66, v66, v90
	v_mul_f32_e32 v67, v67, v90
	v_mul_f32_e32 v68, v68, v91
	v_mul_f32_e32 v69, v69, v91
	v_mul_f32_e32 v70, v70, v91
	v_mul_f32_e32 v71, v71, v91
	v_mul_f32_e32 v72, v72, v92
	v_mul_f32_e32 v73, v73, v92
	v_mul_f32_e32 v74, v74, v92
	v_mul_f32_e32 v75, v75, v92
	v_mul_f32_e32 v76, v76, v93
	v_mul_f32_e32 v77, v77, v93
	v_mul_f32_e32 v78, v78, v93
	v_mul_f32_e32 v79, v79, v93
	v_mul_f32_e32 v80, v80, v94
	v_mul_f32_e32 v81, v81, v94
	v_mul_f32_e32 v82, v82, v94
	v_mul_f32_e32 v83, v83, v94
	v_mul_f32_e32 v84, v84, v95
	v_mul_f32_e32 v85, v85, v95
	v_mul_f32_e32 v86, v86, v95
	v_mul_f32_e32 v87, v87, v95
.Lw_ng_f0:
	s_mov_b64 s[92:93], s[76:77]
	v_cvt_pk_bf16_f32 v186, v56, v60
	v_cvt_pk_bf16_f32 v187, v64, v68
	v_cvt_pk_bf16_f32 v188, v72, v76
	v_cvt_pk_bf16_f32 v189, v80, v84
	v_cvt_pk_bf16_f32 v190, v57, v61
	v_cvt_pk_bf16_f32 v191, v65, v69
	v_cvt_pk_bf16_f32 v192, v73, v77
	v_cvt_pk_bf16_f32 v193, v81, v85
	v_cvt_pk_bf16_f32 v194, v58, v62
	v_cvt_pk_bf16_f32 v195, v66, v70
	v_cvt_pk_bf16_f32 v196, v74, v78
	v_cvt_pk_bf16_f32 v197, v82, v86
	v_cvt_pk_bf16_f32 v198, v59, v63
	v_cvt_pk_bf16_f32 v199, v67, v71
	v_cvt_pk_bf16_f32 v200, v75, v79
	v_cvt_pk_bf16_f32 v201, v83, v87
	ds_write_b128 v220, v[186:189] offset:0
	ds_write_b128 v220, v[190:193] offset:144
	ds_write_b128 v220, v[194:197] offset:288
	ds_write_b128 v220, v[198:201] offset:432
	s_lshl_b32 s97, s78, 3
	s_waitcnt lgkmcnt(0)
	s_barrier
	ds_read_b128 v[202:205], v223 offset:0
	ds_read_b128 v[206:209], v223 offset:1152
	ds_read_b128 v[210:213], v223 offset:2304
	ds_read_b128 v[214:217], v223 offset:3456
	s_waitcnt lgkmcnt(0)
	global_store_dwordx4 v96, v[202:205], s[92:93]
	s_add_u32 s92, s92, s97
	s_addc_u32 s93, s93, 0
	global_store_dwordx4 v96, v[206:209], s[92:93]
	s_add_u32 s92, s92, s97
	s_addc_u32 s93, s93, 0
	global_store_dwordx4 v96, v[210:213], s[92:93]
	s_add_u32 s92, s92, s97
	s_addc_u32 s93, s93, 0
	global_store_dwordx4 v96, v[214:217], s[92:93]
	s_branch .Lw_flush
.Lw_fl1:
	s_cmp_eq_u32 s83, 0
	s_cbranch_scc1 .Lw_ng_f1
	v_mul_f32_e32 v98, v98, v130
	v_mul_f32_e32 v99, v99, v130
	v_mul_f32_e32 v100, v100, v130
	v_mul_f32_e32 v101, v101, v130
	v_mul_f32_e32 v102, v102, v131
	v_mul_f32_e32 v103, v103, v131
	v_mul_f32_e32 v104, v104, v131
	v_mul_f32_e32 v105, v105, v131
	v_mul_f32_e32 v106, v106, v132
	v_mul_f32_e32 v107, v107, v132
	v_mul_f32_e32 v108, v108, v132
	v_mul_f32_e32 v109, v109, v132
	v_mul_f32_e32 v110, v110, v133
	v_mul_f32_e32 v111, v111, v133
	v_mul_f32_e32 v112, v112, v133
	v_mul_f32_e32 v113, v113, v133
	v_mul_f32_e32 v114, v114, v134
	v_mul_f32_e32 v115, v115, v134
	v_mul_f32_e32 v116, v116, v134
	v_mul_f32_e32 v117, v117, v134
	v_mul_f32_e32 v118, v118, v135
	v_mul_f32_e32 v119, v119, v135
	v_mul_f32_e32 v120, v120, v135
	v_mul_f32_e32 v121, v121, v135
	v_mul_f32_e32 v122, v122, v136
	v_mul_f32_e32 v123, v123, v136
	v_mul_f32_e32 v124, v124, v136
	v_mul_f32_e32 v125, v125, v136
	v_mul_f32_e32 v126, v126, v137
	v_mul_f32_e32 v127, v127, v137
	v_mul_f32_e32 v128, v128, v137
	v_mul_f32_e32 v129, v129, v137
.Lw_ng_f1:
	s_mov_b64 s[92:93], s[80:81]
	v_cvt_pk_bf16_f32 v186, v98, v102
	v_cvt_pk_bf16_f32 v187, v106, v110
	v_cvt_pk_bf16_f32 v188, v114, v118
	v_cvt_pk_bf16_f32 v189, v122, v126
	v_cvt_pk_bf16_f32 v190, v99, v103
	v_cvt_pk_bf16_f32 v191, v107, v111
	v_cvt_pk_bf16_f32 v192, v115, v119
	v_cvt_pk_bf16_f32 v193, v123, v127
	v_cvt_pk_bf16_f32 v194, v100, v104
	v_cvt_pk_bf16_f32 v195, v108, v112
	v_cvt_pk_bf16_f32 v196, v116, v120
	v_cvt_pk_bf16_f32 v197, v124, v128
	v_cvt_pk_bf16_f32 v198, v101, v105
	v_cvt_pk_bf16_f32 v199, v109, v113
	v_cvt_pk_bf16_f32 v200, v117, v121
	v_cvt_pk_bf16_f32 v201, v125, v129
	ds_write_b128 v221, v[186:189] offset:0
	ds_write_b128 v221, v[190:193] offset:144
	ds_write_b128 v221, v[194:197] offset:288
	ds_write_b128 v221, v[198:201] offset:432
	s_lshl_b32 s97, s82, 3
	s_waitcnt lgkmcnt(0)
	s_barrier
	ds_read_b128 v[202:205], v224 offset:0
	ds_read_b128 v[206:209], v224 offset:1152
	ds_read_b128 v[210:213], v224 offset:2304
	ds_read_b128 v[214:217], v224 offset:3456
	s_waitcnt lgkmcnt(0)
	global_store_dwordx4 v138, v[202:205], s[92:93]
	s_add_u32 s92, s92, s97
	s_addc_u32 s93, s93, 0
	global_store_dwordx4 v138, v[206:209], s[92:93]
	s_add_u32 s92, s92, s97
	s_addc_u32 s93, s93, 0
	global_store_dwordx4 v138, v[210:213], s[92:93]
	s_add_u32 s92, s92, s97
	s_addc_u32 s93, s93, 0
	global_store_dwordx4 v138, v[214:217], s[92:93]
	s_branch .Lw_flush
.Lw_fl2:
	s_cmp_eq_u32 s91, 0
	s_cbranch_scc1 .Lw_ng_f2
	v_mul_f32_e32 v140, v140, v172
	v_mul_f32_e32 v141, v141, v172
	v_mul_f32_e32 v142, v142, v172
	v_mul_f32_e32 v143, v143, v172
	v_mul_f32_e32 v144, v144, v173
	v_mul_f32_e32 v145, v145, v173
	v_mul_f32_e32 v146, v146, v173
	v_mul_f32_e32 v147, v147, v173
	v_mul_f32_e32 v148, v148, v174
	v_mul_f32_e32 v149, v149, v174
	v_mul_f32_e32 v150, v150, v174
	v_mul_f32_e32 v151, v151, v174
	v_mul_f32_e32 v152, v152, v175
	v_mul_f32_e32 v153, v153, v175
	v_mul_f32_e32 v154, v154, v175
	v_mul_f32_e32 v155, v155, v175
	v_mul_f32_e32 v156, v156, v176
	v_mul_f32_e32 v157, v157, v176
	v_mul_f32_e32 v158, v158, v176
	v_mul_f32_e32 v159, v159, v176
	v_mul_f32_e32 v160, v160, v177
	v_mul_f32_e32 v161, v161, v177
	v_mul_f32_e32 v162, v162, v177
	v_mul_f32_e32 v163, v163, v177
	v_mul_f32_e32 v164, v164, v178
	v_mul_f32_e32 v165, v165, v178
	v_mul_f32_e32 v166, v166, v178
	v_mul_f32_e32 v167, v167, v178
	v_mul_f32_e32 v168, v168, v179
	v_mul_f32_e32 v169, v169, v179
	v_mul_f32_e32 v170, v170, v179
	v_mul_f32_e32 v171, v171, v179
.Lw_ng_f2:
	s_mov_b64 s[92:93], s[88:89]
	v_cvt_pk_bf16_f32 v186, v140, v144
	v_cvt_pk_bf16_f32 v187, v148, v152
	v_cvt_pk_bf16_f32 v188, v156, v160
	v_cvt_pk_bf16_f32 v189, v164, v168
	v_cvt_pk_bf16_f32 v190, v141, v145
	v_cvt_pk_bf16_f32 v191, v149, v153
	v_cvt_pk_bf16_f32 v192, v157, v161
	v_cvt_pk_bf16_f32 v193, v165, v169
	v_cvt_pk_bf16_f32 v194, v142, v146
	v_cvt_pk_bf16_f32 v195, v150, v154
	v_cvt_pk_bf16_f32 v196, v158, v162
	v_cvt_pk_bf16_f32 v197, v166, v170
	v_cvt_pk_bf16_f32 v198, v143, v147
	v_cvt_pk_bf16_f32 v199, v151, v155
	v_cvt_pk_bf16_f32 v200, v159, v163
	v_cvt_pk_bf16_f32 v201, v167, v171
	ds_write_b128 v222, v[186:189] offset:0
	ds_write_b128 v222, v[190:193] offset:144
	ds_write_b128 v222, v[194:197] offset:288
	ds_write_b128 v222, v[198:201] offset:432
	s_lshl_b32 s97, s90, 3
	s_waitcnt lgkmcnt(0)
	s_barrier
	ds_read_b128 v[202:205], v225 offset:0
	ds_read_b128 v[206:209], v225 offset:1152
	ds_read_b128 v[210:213], v225 offset:2304
	ds_read_b128 v[214:217], v225 offset:3456
	s_waitcnt lgkmcnt(0)
	global_store_dwordx4 v180, v[202:205], s[92:93]
	s_add_u32 s92, s92, s97
	s_addc_u32 s93, s93, 0
	global_store_dwordx4 v180, v[206:209], s[92:93]
	s_add_u32 s92, s92, s97
	s_addc_u32 s93, s93, 0
	global_store_dwordx4 v180, v[210:213], s[92:93]
	s_add_u32 s92, s92, s97
	s_addc_u32 s93, s93, 0
	global_store_dwordx4 v180, v[214:217], s[92:93]
	s_branch .Lw_flush
